# NA and GQA units skip the bias-LUT refill when the previous unit of the workgroup used the same head or group (LUT still valid in LDS)
# baseline (speedup 1.0000x reference)
; template <int MODE, bool FROZEN = false>
; __device__ __forceinline__ bool attn_unit(LAS unsigned char* lds, const Params& p, int l, int ua, int ub) {
;     ...
;         const int h = ua, R0 = ub * 4; myrow = R0 + (wid >> 1); qtok0 = myrow * 64 + (wid & 1) * 32;
;         qcol = h * 64; kcol = 512 + h * 64; vcol = h * 64; ocol = h * 64;
;         const int rs_first = min(max(R0 - 4, 0), 248), rs_last = min(max(R0 + 3 - 4, 0), 248), my_rs = min(max(myrow - 4, 0), 248);
;         kt0 = rs_first * 64; NT = rs_last + 8 - rs_first; wt_lo = my_rs - rs_first; wt_hi = wt_lo + 8;
;         for (int i = tid; i < 15 * 127; i += 512) { const int dr_ = i / 127, dc_ = min(max(i % 127 - 48, 0), 30); lut[i] = p.na_rpb[(size_t)(l * 8 + h) * 465 + dr_ * 31 + dc_] * LOG2E; }
.LBB0_180:
	v_mov_b32_e32 v0, v228
	s_movk_i32 s0, 0x771
	s_and_b32 s8, s14, 7
	s_nop 0
	v_readfirstlane_b32 s15, v0
	v_cmp_gt_i32_e32 vcc, s0, v0
	s_and_saveexec_b64 s[0:1], vcc
	s_cbranch_execz .LBB0_188
	s_cmp_eq_u32 s14, s33
	s_cbranch_scc1 .Lna_lut_fill
	s_sub_i32 s100, s14, s30
	s_xor_b32 s100, s100, s14
	s_and_b32 s100, s100, 7
	s_cmp_eq_u32 s100, 0
	s_cbranch_scc1 .LBB0_188
.Lna_lut_fill:
	v_readlane_b32 s4, v255, 13
	s_or_b32 s4, s8, s4
	v_readlane_b32 s40, v254, 57
	v_max_i32_e32 v1, 0x571, v0
	s_mul_hi_i32 s5, s4, 0x744
	s_mulk_i32 s4, 0x744
	v_readlane_b32 s46, v254, 63
	v_sub_u32_e32 v1, v1, v0
	v_readlane_b32 s47, v255, 0
	s_add_u32 s4, s46, s4
	v_add_u32_e32 v1, 0x1ff, v1
	s_movk_i32 s10, 0x1ff
	s_addc_u32 s5, s47, s5
	v_cmp_lt_u32_e32 vcc, s10, v1
	s_mov_b64 s[12:13], -1
	v_mov_b32_e32 v2, v0
	v_readlane_b32 s41, v254, 58
	v_readlane_b32 s42, v254, 59
	v_readlane_b32 s43, v254, 60
	v_readlane_b32 s44, v254, 61
	v_readlane_b32 s45, v254, 62
	v_readlane_b32 s48, v255, 1
	v_readlane_b32 s49, v255, 2
	v_readlane_b32 s50, v255, 3
	v_readlane_b32 s51, v255, 4
	v_readlane_b32 s52, v255, 5
	v_readlane_b32 s53, v255, 6
	v_readlane_b32 s54, v255, 7
	v_readlane_b32 s55, v255, 8
	s_and_saveexec_b64 s[10:11], vcc
	s_cbranch_execz .LBB0_185
	v_lshrrev_b32_e32 v1, 9, v1
	v_add_u32_e32 v4, 1, v1
	v_and_b32_e32 v5, 0xfffffe, v4
	v_add_u32_e32 v1, 0x200, v0
	v_readlane_b32 s12, v254, 48
	v_mov_b32_e32 v7, v5
	v_mov_b64_e32 v[2:3], v[0:1]
	v_lshl_add_u32 v6, v0, 2, s12
	s_mov_b64 s[12:13], 0
	s_movk_i32 s16, 0x7f
	s_mov_b32 s17, 0x81020409
	s_mov_b32 s18, 0x3fb8aa3b

; template <int MODE, bool FROZEN = false>
; __device__ __forceinline__ bool attn_unit(LAS unsigned char* lds, const Params& p, int l, int ua, int ub) {
;     ...
;         const int g = ua, qb = ub, hq = g * 4 + (wid >> 1); qtok0 = qb * 64 + (wid & 1) * 32; lut_sel = wid >> 1;
;         qcol = 3072 + hq * 64; kcol = 3584 + g * 64; vcol = 1024 + g * 64; ocol = hq * 64;
;         const int tlo = max(qb - 2, 0), thi = min(qb + 2, S / 64 - 1); kt0 = tlo * 64; NT = thi - tlo + 1; wt_hi = NT;
;         for (int i = tid; i < 4 * 449; i += 512) { const int hh = i / 449, rel = i % 449 - 224; lut[i] = (rel >= -128 && rel <= 128) ? p.rel_bias[t5_bucket(rel) * 12 + 4 + g * 4 + hh] * LOG2E : NEGBIG; }
.LBB0_490:
	s_and_b32 s22, s20, 1
	v_mov_b32_e32 v2, v228
	s_movk_i32 s0, 0x704
	s_lshl_b32 s8, s22, 2
	v_readfirstlane_b32 s21, v2
	v_cmp_gt_i32_e32 vcc, s0, v2
	s_and_saveexec_b64 s[0:1], vcc
	s_cbranch_execz .LBB0_503
	s_cmp_eq_u32 s20, s33
	s_cbranch_scc1 .Lgqa_lut_fill
	s_sub_i32 s100, s20, s30
	s_xor_b32 s100, s100, s20
	s_and_b32 s100, s100, 1
	s_cmp_eq_u32 s100, 0
	s_cbranch_scc1 .LBB0_503
.Lgqa_lut_fill:
	v_readlane_b32 s4, v254, 48
	v_mov_b32_e32 v4, v2
	s_nop 0
	v_lshl_add_u32 v3, v2, 2, s4
	s_mov_b64 s[4:5], 0
	s_branch .LBB0_497
